# grid barrier poll loops: s_sleep 1 replaced by s_nop 0 (faster flag detection)
# speedup vs baseline: 1.0026x; 1.0026x over previous
.LBB0_156:
	global_load_dword v16, v17, s[8:9] sc1
	s_waitcnt lgkmcnt(0)
	global_load_dword v1, v17, s[10:11] sc1
	global_load_dword v2, v17, s[12:13] sc1
	global_load_dword v3, v17, s[14:15] sc1
	global_load_dword v4, v17, s[16:17] sc1
	global_load_dword v5, v17, s[18:19] sc1
	global_load_dword v6, v17, s[22:23] sc1
	global_load_dword v7, v17, s[24:25] sc1
	global_load_dword v8, v17, s[38:39] sc1
	global_load_dword v9, v17, s[40:41] sc1
	global_load_dword v10, v17, s[42:43] sc1
	global_load_dword v11, v17, s[44:45] sc1
	global_load_dword v12, v17, s[46:47] sc1
	global_load_dword v13, v17, s[48:49] sc1
	global_load_dword v14, v17, s[50:51] sc1
	global_load_dword v15, v17, s[52:53] sc1
	s_mov_b64 s[54:55], -1
	s_mov_b64 s[56:57], -1
	s_waitcnt vmcnt(14)
	v_add_u32_e32 v18, v1, v16
	s_waitcnt vmcnt(13)
	v_add_u32_e32 v18, v18, v2
	s_waitcnt vmcnt(12)
	v_add_u32_e32 v18, v18, v3
	s_waitcnt vmcnt(11)
	v_add_u32_e32 v18, v18, v4
	s_waitcnt vmcnt(10)
	v_add_u32_e32 v18, v18, v5
	s_waitcnt vmcnt(9)
	v_add_u32_e32 v18, v18, v6
	s_waitcnt vmcnt(8)
	v_add_u32_e32 v18, v18, v7
	s_waitcnt vmcnt(7)
	v_add_u32_e32 v18, v18, v8
	s_waitcnt vmcnt(6)
	v_add_u32_e32 v18, v18, v9
	s_waitcnt vmcnt(5)
	v_add_u32_e32 v18, v18, v10
	s_waitcnt vmcnt(4)
	v_add_u32_e32 v18, v18, v11
	s_waitcnt vmcnt(3)
	v_add_u32_e32 v18, v18, v12
	s_waitcnt vmcnt(2)
	v_add_u32_e32 v18, v18, v13
	s_waitcnt vmcnt(1)
	v_add_u32_e32 v18, v18, v14
	s_waitcnt vmcnt(0)
	v_add_u32_e32 v18, v18, v15
	v_cmp_eq_u32_e32 vcc, s37, v18
	s_cbranch_vccnz .LBB0_155
	s_and_b32 s54, s60, 0xff
	s_cmp_eq_u32 s54, 0
	s_mov_b64 s[54:55], -1
	s_mov_b64 s[58:59], -1
	s_nop 0
	s_cbranch_scc0 .LBB0_160
	global_load_dword v18, v17, s[6:7] sc1
	s_waitcnt vmcnt(0)
	v_cmp_eq_u32_e32 vcc, 0, v18
	s_cbranch_vccnz .LBB0_162
	s_mov_b64 s[58:59], 0

.LBB0_174:
	s_and_b32 s24, s37, 0xff
	s_mov_b64 s[22:23], -1
	s_cmp_lg_u32 s24, 0
	s_mov_b64 s[38:39], -1
	s_nop 0
	s_cbranch_scc1 .LBB0_177
	global_load_dword v3, v1, s[12:13] sc1
	s_waitcnt vmcnt(0)
	v_cmp_eq_u32_e32 vcc, 0, v3
	s_cbranch_vccnz .LBB0_179
	s_mov_b64 s[38:39], 0
	s_mov_b64 s[24:25], -1

.LBB0_191:
	s_and_b32 s22, s37, 0xff
	s_cmp_lg_u32 s22, 0
	s_mov_b64 s[24:25], -1
	s_nop 0
	s_cbranch_scc1 .LBB0_194
	global_load_dword v2, v1, s[12:13] sc1
	s_waitcnt vmcnt(0)
	v_cmp_eq_u32_e32 vcc, 0, v2
	s_cbranch_vccnz .LBB0_196
	s_mov_b64 s[24:25], 0
	s_mov_b64 s[22:23], -1

.LBB0_211:
	global_load_dword v17, v18, s[8:9] sc1
	global_load_dword v2, v18, s[10:11] sc1
	global_load_dword v3, v18, s[12:13] sc1
	global_load_dword v4, v18, s[14:15] sc1
	global_load_dword v5, v18, s[16:17] sc1
	global_load_dword v6, v18, s[18:19] sc1
	global_load_dword v7, v18, s[22:23] sc1
	global_load_dword v8, v18, s[24:25] sc1
	global_load_dword v9, v18, s[38:39] sc1
	global_load_dword v10, v18, s[40:41] sc1
	global_load_dword v11, v18, s[42:43] sc1
	global_load_dword v12, v18, s[44:45] sc1
	global_load_dword v13, v18, s[46:47] sc1
	global_load_dword v14, v18, s[48:49] sc1
	global_load_dword v15, v18, s[50:51] sc1
	global_load_dword v16, v18, s[52:53] sc1
	s_mov_b64 s[54:55], -1
	s_mov_b64 s[56:57], -1
	s_waitcnt vmcnt(14)
	v_add_u32_e32 v19, v2, v17
	s_waitcnt vmcnt(13)
	v_add_u32_e32 v19, v19, v3
	s_waitcnt vmcnt(12)
	v_add_u32_e32 v19, v19, v4
	s_waitcnt vmcnt(11)
	v_add_u32_e32 v19, v19, v5
	s_waitcnt vmcnt(10)
	v_add_u32_e32 v19, v19, v6
	s_waitcnt vmcnt(9)
	v_add_u32_e32 v19, v19, v7
	s_waitcnt vmcnt(8)
	v_add_u32_e32 v19, v19, v8
	s_waitcnt vmcnt(7)
	v_add_u32_e32 v19, v19, v9
	s_waitcnt vmcnt(6)
	v_add_u32_e32 v19, v19, v10
	s_waitcnt vmcnt(5)
	v_add_u32_e32 v19, v19, v11
	s_waitcnt vmcnt(4)
	v_add_u32_e32 v19, v19, v12
	s_waitcnt vmcnt(3)
	v_add_u32_e32 v19, v19, v13
	s_waitcnt vmcnt(2)
	v_add_u32_e32 v19, v19, v14
	s_waitcnt vmcnt(1)
	v_add_u32_e32 v19, v19, v15
	s_waitcnt vmcnt(0)
	v_add_u32_e32 v19, v19, v16
	v_cmp_eq_u32_e32 vcc, s60, v19
	s_cbranch_vccnz .LBB0_210
	s_and_b32 s54, s37, 0xff
	s_cmp_eq_u32 s54, 0
	s_mov_b64 s[54:55], -1
	s_mov_b64 s[58:59], -1
	s_nop 0
	s_cbranch_scc0 .LBB0_215
	global_load_dword v19, v18, s[6:7] sc1
	s_waitcnt vmcnt(0)
	v_cmp_eq_u32_e32 vcc, 0, v19
	s_cbranch_vccnz .LBB0_217
	s_mov_b64 s[58:59], 0

.LBB0_229:
	s_and_b32 s24, s37, 0xff
	s_mov_b64 s[22:23], -1
	s_cmp_lg_u32 s24, 0
	s_mov_b64 s[38:39], -1
	s_nop 0
	s_cbranch_scc1 .LBB0_232
	global_load_dword v4, v2, s[12:13] sc1
	s_waitcnt vmcnt(0)
	v_cmp_eq_u32_e32 vcc, 0, v4
	s_cbranch_vccnz .LBB0_234
	s_mov_b64 s[38:39], 0
	s_mov_b64 s[24:25], -1

.LBB0_246:
	s_and_b32 s22, s37, 0xff
	s_cmp_lg_u32 s22, 0
	s_mov_b64 s[24:25], -1
	s_nop 0
	s_cbranch_scc1 .LBB0_249
	global_load_dword v3, v2, s[12:13] sc1
	s_waitcnt vmcnt(0)
	v_cmp_eq_u32_e32 vcc, 0, v3
	s_cbranch_vccnz .LBB0_251
	s_mov_b64 s[24:25], 0
	s_mov_b64 s[22:23], -1

.LBB0_632:
	global_load_dword v17, v18, s[8:9] sc1
	global_load_dword v2, v18, s[10:11] sc1
	global_load_dword v3, v18, s[12:13] sc1
	global_load_dword v4, v18, s[14:15] sc1
	global_load_dword v5, v18, s[16:17] sc1
	global_load_dword v6, v18, s[18:19] sc1
	global_load_dword v7, v18, s[22:23] sc1
	global_load_dword v8, v18, s[24:25] sc1
	global_load_dword v9, v18, s[44:45] sc1
	global_load_dword v10, v18, s[46:47] sc1
	global_load_dword v11, v18, s[48:49] sc1
	global_load_dword v12, v18, s[50:51] sc1
	global_load_dword v13, v18, s[52:53] sc1
	global_load_dword v14, v18, s[54:55] sc1
	global_load_dword v15, v18, s[56:57] sc1
	global_load_dword v16, v18, s[58:59] sc1
	s_mov_b64 s[60:61], -1
	s_mov_b64 s[62:63], -1
	s_waitcnt vmcnt(14)
	v_add_u32_e32 v19, v2, v17
	s_waitcnt vmcnt(13)
	v_add_u32_e32 v19, v19, v3
	s_waitcnt vmcnt(12)
	v_add_u32_e32 v19, v19, v4
	s_waitcnt vmcnt(11)
	v_add_u32_e32 v19, v19, v5
	s_waitcnt vmcnt(10)
	v_add_u32_e32 v19, v19, v6
	s_waitcnt vmcnt(9)
	v_add_u32_e32 v19, v19, v7
	s_waitcnt vmcnt(8)
	v_add_u32_e32 v19, v19, v8
	s_waitcnt vmcnt(7)
	v_add_u32_e32 v19, v19, v9
	s_waitcnt vmcnt(6)
	v_add_u32_e32 v19, v19, v10
	s_waitcnt vmcnt(5)
	v_add_u32_e32 v19, v19, v11
	s_waitcnt vmcnt(4)
	v_add_u32_e32 v19, v19, v12
	s_waitcnt vmcnt(3)
	v_add_u32_e32 v19, v19, v13
	s_waitcnt vmcnt(2)
	v_add_u32_e32 v19, v19, v14
	s_waitcnt vmcnt(1)
	v_add_u32_e32 v19, v19, v15
	s_waitcnt vmcnt(0)
	v_add_u32_e32 v19, v19, v16
	v_cmp_eq_u32_e32 vcc, s67, v19
	s_cbranch_vccnz .LBB0_631
	s_and_b32 s33, s66, 0xff
	s_cmp_eq_u32 s33, 0
	s_mov_b64 s[64:65], -1
	s_nop 0
	s_cbranch_scc0 .LBB0_636
	global_load_dword v19, v18, s[6:7] sc1
	s_waitcnt vmcnt(0)
	v_cmp_eq_u32_e32 vcc, 0, v19
	s_cbranch_vccnz .LBB0_638
	s_mov_b64 s[64:65], 0

.LBB0_650:
	s_and_b32 s24, s46, 0xff
	s_mov_b64 s[22:23], -1
	s_cmp_lg_u32 s24, 0
	s_mov_b64 s[44:45], -1
	s_nop 0
	s_cbranch_scc1 .LBB0_653
	global_load_dword v4, v2, s[12:13] sc1
	s_waitcnt vmcnt(0)
	v_cmp_eq_u32_e32 vcc, 0, v4
	s_cbranch_vccnz .LBB0_655
	s_mov_b64 s[44:45], 0
	s_mov_b64 s[24:25], -1

.LBB0_667:
	s_and_b32 s22, s46, 0xff
	s_cmp_lg_u32 s22, 0
	s_mov_b64 s[24:25], -1
	s_nop 0
	s_cbranch_scc1 .LBB0_670
	global_load_dword v3, v2, s[12:13] sc1
	s_waitcnt vmcnt(0)
	v_cmp_eq_u32_e32 vcc, 0, v3
	s_cbranch_vccnz .LBB0_672
	s_mov_b64 s[24:25], 0
	s_mov_b64 s[22:23], -1

.LBB0_927:
	global_load_dword v16, v17, s[8:9] sc1
	global_load_dword v1, v17, s[10:11] sc1
	global_load_dword v2, v17, s[12:13] sc1
	global_load_dword v3, v17, s[14:15] sc1
	global_load_dword v4, v17, s[16:17] sc1
	global_load_dword v5, v17, s[18:19] sc1
	global_load_dword v6, v17, s[22:23] sc1
	global_load_dword v7, v17, s[24:25] sc1
	global_load_dword v8, v17, s[40:41] sc1
	global_load_dword v9, v17, s[42:43] sc1
	global_load_dword v10, v17, s[48:49] sc1
	global_load_dword v11, v17, s[50:51] sc1
	global_load_dword v12, v17, s[52:53] sc1
	global_load_dword v13, v17, s[54:55] sc1
	global_load_dword v14, v17, s[56:57] sc1
	global_load_dword v15, v17, s[58:59] sc1
	s_mov_b64 s[60:61], -1
	s_mov_b64 s[62:63], -1
	s_waitcnt vmcnt(14)
	v_add_u32_e32 v18, v1, v16
	s_waitcnt vmcnt(13)
	v_add_u32_e32 v18, v18, v2
	s_waitcnt vmcnt(12)
	v_add_u32_e32 v18, v18, v3
	s_waitcnt vmcnt(11)
	v_add_u32_e32 v18, v18, v4
	s_waitcnt vmcnt(10)
	v_add_u32_e32 v18, v18, v5
	s_waitcnt vmcnt(9)
	v_add_u32_e32 v18, v18, v6
	s_waitcnt vmcnt(8)
	v_add_u32_e32 v18, v18, v7
	s_waitcnt vmcnt(7)
	v_add_u32_e32 v18, v18, v8
	s_waitcnt vmcnt(6)
	v_add_u32_e32 v18, v18, v9
	s_waitcnt vmcnt(5)
	v_add_u32_e32 v18, v18, v10
	s_waitcnt vmcnt(4)
	v_add_u32_e32 v18, v18, v11
	s_waitcnt vmcnt(3)
	v_add_u32_e32 v18, v18, v12
	s_waitcnt vmcnt(2)
	v_add_u32_e32 v18, v18, v13
	s_waitcnt vmcnt(1)
	v_add_u32_e32 v18, v18, v14
	s_waitcnt vmcnt(0)
	v_add_u32_e32 v18, v18, v15
	v_cmp_eq_u32_e32 vcc, s67, v18
	s_cbranch_vccnz .LBB0_926
	s_and_b32 s33, s66, 0xff
	s_cmp_eq_u32 s33, 0
	s_mov_b64 s[64:65], -1
	s_nop 0
	s_cbranch_scc0 .LBB0_931
	global_load_dword v18, v17, s[6:7] sc1
	s_waitcnt vmcnt(0)
	v_cmp_eq_u32_e32 vcc, 0, v18
	s_cbranch_vccnz .LBB0_933
	s_mov_b64 s[64:65], 0

.LBB0_945:
	s_and_b32 s24, s42, 0xff
	s_mov_b64 s[22:23], -1
	s_cmp_lg_u32 s24, 0
	s_mov_b64 s[40:41], -1
	s_nop 0
	s_cbranch_scc1 .LBB0_948
	global_load_dword v3, v1, s[12:13] sc1
	s_waitcnt vmcnt(0)
	v_cmp_eq_u32_e32 vcc, 0, v3
	s_cbranch_vccnz .LBB0_950
	s_mov_b64 s[40:41], 0
	s_mov_b64 s[24:25], -1

.LBB0_962:
	s_and_b32 s22, s42, 0xff
	s_cmp_lg_u32 s22, 0
	s_mov_b64 s[24:25], -1
	s_nop 0
	s_cbranch_scc1 .LBB0_965
	global_load_dword v2, v1, s[12:13] sc1
	s_waitcnt vmcnt(0)
	v_cmp_eq_u32_e32 vcc, 0, v2
	s_cbranch_vccnz .LBB0_967
	s_mov_b64 s[24:25], 0
	s_mov_b64 s[22:23], -1

.LBB0_984:
	global_load_dword v16, v17, s[8:9] sc1
	global_load_dword v1, v17, s[10:11] sc1
	global_load_dword v2, v17, s[12:13] sc1
	global_load_dword v3, v17, s[14:15] sc1
	global_load_dword v4, v17, s[16:17] sc1
	global_load_dword v5, v17, s[18:19] sc1
	global_load_dword v6, v17, s[22:23] sc1
	global_load_dword v7, v17, s[24:25] sc1
	global_load_dword v8, v17, s[40:41] sc1
	global_load_dword v9, v17, s[42:43] sc1
	global_load_dword v10, v17, s[44:45] sc1
	global_load_dword v11, v17, s[46:47] sc1
	global_load_dword v12, v17, s[48:49] sc1
	global_load_dword v13, v17, s[50:51] sc1
	global_load_dword v14, v17, s[52:53] sc1
	global_load_dword v15, v17, s[54:55] sc1
	s_mov_b64 s[56:57], -1
	s_mov_b64 s[58:59], -1
	s_waitcnt vmcnt(14)
	v_add_u32_e32 v18, v1, v16
	s_waitcnt vmcnt(13)
	v_add_u32_e32 v18, v18, v2
	s_waitcnt vmcnt(12)
	v_add_u32_e32 v18, v18, v3
	s_waitcnt vmcnt(11)
	v_add_u32_e32 v18, v18, v4
	s_waitcnt vmcnt(10)
	v_add_u32_e32 v18, v18, v5
	s_waitcnt vmcnt(9)
	v_add_u32_e32 v18, v18, v6
	s_waitcnt vmcnt(8)
	v_add_u32_e32 v18, v18, v7
	s_waitcnt vmcnt(7)
	v_add_u32_e32 v18, v18, v8
	s_waitcnt vmcnt(6)
	v_add_u32_e32 v18, v18, v9
	s_waitcnt vmcnt(5)
	v_add_u32_e32 v18, v18, v10
	s_waitcnt vmcnt(4)
	v_add_u32_e32 v18, v18, v11
	s_waitcnt vmcnt(3)
	v_add_u32_e32 v18, v18, v12
	s_waitcnt vmcnt(2)
	v_add_u32_e32 v18, v18, v13
	s_waitcnt vmcnt(1)
	v_add_u32_e32 v18, v18, v14
	s_waitcnt vmcnt(0)
	v_add_u32_e32 v18, v18, v15
	v_cmp_eq_u32_e32 vcc, s64, v18
	s_cbranch_vccnz .LBB0_983
	s_and_b32 s33, s37, 0xff
	s_cmp_eq_u32 s33, 0
	s_mov_b64 s[60:61], -1
	s_nop 0
	s_cbranch_scc0 .LBB0_988
	global_load_dword v18, v17, s[6:7] sc1
	s_waitcnt vmcnt(0)
	v_cmp_eq_u32_e32 vcc, 0, v18
	s_cbranch_vccnz .LBB0_990
	s_mov_b64 s[60:61], 0

.LBB0_1002:
	s_and_b32 s24, s37, 0xff
	s_mov_b64 s[22:23], -1
	s_cmp_lg_u32 s24, 0
	s_mov_b64 s[40:41], -1
	s_nop 0
	s_cbranch_scc1 .LBB0_1005
	global_load_dword v3, v1, s[12:13] sc1
	s_waitcnt vmcnt(0)
	v_cmp_eq_u32_e32 vcc, 0, v3
	s_cbranch_vccnz .LBB0_1007
	s_mov_b64 s[40:41], 0
	s_mov_b64 s[24:25], -1

.LBB0_1060:
	global_load_dword v17, v18, s[10:11] sc1
	global_load_dword v2, v18, s[14:15] sc1
	global_load_dword v3, v18, s[16:17] sc1
	global_load_dword v4, v18, s[18:19] sc1
	global_load_dword v5, v18, s[22:23] sc1
	global_load_dword v6, v18, s[24:25] sc1
	global_load_dword v7, v18, s[40:41] sc1
	global_load_dword v8, v18, s[42:43] sc1
	global_load_dword v9, v18, s[44:45] sc1
	global_load_dword v10, v18, s[46:47] sc1
	global_load_dword v11, v18, s[48:49] sc1
	global_load_dword v12, v18, s[50:51] sc1
	global_load_dword v13, v18, s[52:53] sc1
	global_load_dword v14, v18, s[54:55] sc1
	global_load_dword v15, v18, s[56:57] sc1
	global_load_dword v16, v18, s[58:59] sc1
	s_mov_b64 s[60:61], -1
	s_mov_b64 s[62:63], -1
	s_waitcnt vmcnt(14)
	v_add_u32_e32 v19, v2, v17
	s_waitcnt vmcnt(13)
	v_add_u32_e32 v19, v19, v3
	s_waitcnt vmcnt(12)
	v_add_u32_e32 v19, v19, v4
	s_waitcnt vmcnt(11)
	v_add_u32_e32 v19, v19, v5
	s_waitcnt vmcnt(10)
	v_add_u32_e32 v19, v19, v6
	s_waitcnt vmcnt(9)
	v_add_u32_e32 v19, v19, v7
	s_waitcnt vmcnt(8)
	v_add_u32_e32 v19, v19, v8
	s_waitcnt vmcnt(7)
	v_add_u32_e32 v19, v19, v9
	s_waitcnt vmcnt(6)
	v_add_u32_e32 v19, v19, v10
	s_waitcnt vmcnt(5)
	v_add_u32_e32 v19, v19, v11
	s_waitcnt vmcnt(4)
	v_add_u32_e32 v19, v19, v12
	s_waitcnt vmcnt(3)
	v_add_u32_e32 v19, v19, v13
	s_waitcnt vmcnt(2)
	v_add_u32_e32 v19, v19, v14
	s_waitcnt vmcnt(1)
	v_add_u32_e32 v19, v19, v15
	s_waitcnt vmcnt(0)
	v_add_u32_e32 v19, v19, v16
	v_cmp_eq_u32_e32 vcc, s66, v19
	s_cbranch_vccnz .LBB0_1059
	s_and_b32 s33, s37, 0xff
	s_cmp_eq_u32 s33, 0
	s_mov_b64 s[64:65], -1
	s_nop 0
	s_cbranch_scc0 .LBB0_1064
	global_load_dword v19, v18, s[8:9] sc1
	s_waitcnt vmcnt(0)
	v_cmp_eq_u32_e32 vcc, 0, v19
	s_cbranch_vccnz .LBB0_1066
	s_mov_b64 s[64:65], 0

.LBB0_1078:
	s_and_b32 s33, s37, 0xff
	s_mov_b64 s[40:41], -1
	s_cmp_lg_u32 s33, 0
	s_mov_b64 s[44:45], -1
	s_nop 0
	s_cbranch_scc1 .LBB0_1081
	global_load_dword v4, v2, s[16:17] sc1
	s_waitcnt vmcnt(0)
	v_cmp_eq_u32_e32 vcc, 0, v4
	s_cbranch_vccnz .LBB0_1083
	s_mov_b64 s[44:45], 0
	s_mov_b64 s[42:43], -1

.LBB0_1095:
	s_and_b32 s33, s37, 0xff
	s_cmp_lg_u32 s33, 0
	s_mov_b64 s[42:43], -1
	s_nop 0
	s_cbranch_scc1 .LBB0_1098
	global_load_dword v3, v2, s[16:17] sc1
	s_waitcnt vmcnt(0)
	v_cmp_eq_u32_e32 vcc, 0, v3
	s_cbranch_vccnz .LBB0_1100
	s_mov_b64 s[42:43], 0
	s_mov_b64 s[40:41], -1

.LBB0_1183:
	global_load_dword v17, v18, s[14:15] sc1
	global_load_dword v2, v18, s[16:17] sc1
	global_load_dword v3, v18, s[18:19] sc1
	global_load_dword v4, v18, s[22:23] sc1
	global_load_dword v5, v18, s[24:25] sc1
	global_load_dword v6, v18, s[40:41] sc1
	global_load_dword v7, v18, s[42:43] sc1
	global_load_dword v8, v18, s[44:45] sc1
	global_load_dword v9, v18, s[46:47] sc1
	global_load_dword v10, v18, s[48:49] sc1
	global_load_dword v11, v18, s[50:51] sc1
	global_load_dword v12, v18, s[52:53] sc1
	global_load_dword v13, v18, s[54:55] sc1
	global_load_dword v14, v18, s[56:57] sc1
	global_load_dword v15, v18, s[58:59] sc1
	global_load_dword v16, v18, s[60:61] sc1
	s_mov_b64 s[62:63], -1
	s_mov_b64 s[64:65], -1
	s_waitcnt vmcnt(14)
	v_add_u32_e32 v19, v2, v17
	s_waitcnt vmcnt(13)
	v_add_u32_e32 v19, v19, v3
	s_waitcnt vmcnt(12)
	v_add_u32_e32 v19, v19, v4
	s_waitcnt vmcnt(11)
	v_add_u32_e32 v19, v19, v5
	s_waitcnt vmcnt(10)
	v_add_u32_e32 v19, v19, v6
	s_waitcnt vmcnt(9)
	v_add_u32_e32 v19, v19, v7
	s_waitcnt vmcnt(8)
	v_add_u32_e32 v19, v19, v8
	s_waitcnt vmcnt(7)
	v_add_u32_e32 v19, v19, v9
	s_waitcnt vmcnt(6)
	v_add_u32_e32 v19, v19, v10
	s_waitcnt vmcnt(5)
	v_add_u32_e32 v19, v19, v11
	s_waitcnt vmcnt(4)
	v_add_u32_e32 v19, v19, v12
	s_waitcnt vmcnt(3)
	v_add_u32_e32 v19, v19, v13
	s_waitcnt vmcnt(2)
	v_add_u32_e32 v19, v19, v14
	s_waitcnt vmcnt(1)
	v_add_u32_e32 v19, v19, v15
	s_waitcnt vmcnt(0)
	v_add_u32_e32 v19, v19, v16
	v_cmp_eq_u32_e32 vcc, s69, v19
	s_cbranch_vccnz .LBB0_1182
	s_and_b32 s33, s37, 0xff
	s_cmp_eq_u32 s33, 0
	s_mov_b64 s[66:67], -1
	s_nop 0
	s_cbranch_scc0 .LBB0_1187
	global_load_dword v19, v18, s[8:9] sc1
	s_waitcnt vmcnt(0)
	v_cmp_eq_u32_e32 vcc, 0, v19
	s_cbranch_vccnz .LBB0_1189
	s_mov_b64 s[66:67], 0

.LBB0_1201:
	s_and_b32 s33, s37, 0xff
	s_mov_b64 s[42:43], -1
	s_cmp_lg_u32 s33, 0
	s_mov_b64 s[46:47], -1
	s_nop 0
	s_cbranch_scc1 .LBB0_1204
	global_load_dword v4, v2, s[18:19] sc1
	s_waitcnt vmcnt(0)
	v_cmp_eq_u32_e32 vcc, 0, v4
	s_cbranch_vccnz .LBB0_1206
	s_mov_b64 s[46:47], 0
	s_mov_b64 s[44:45], -1

.LBB0_1218:
	s_and_b32 s33, s37, 0xff
	s_cmp_lg_u32 s33, 0
	s_mov_b64 s[44:45], -1
	s_nop 0
	s_cbranch_scc1 .LBB0_1221
	global_load_dword v3, v2, s[18:19] sc1
	s_waitcnt vmcnt(0)
	v_cmp_eq_u32_e32 vcc, 0, v3
	s_cbranch_vccnz .LBB0_1223
	s_mov_b64 s[44:45], 0
	s_mov_b64 s[42:43], -1

.LBB0_1263:
	global_load_dword v17, v18, s[12:13] sc1
	s_waitcnt lgkmcnt(0)
	global_load_dword v2, v18, s[14:15] sc1
	global_load_dword v3, v18, s[16:17] sc1
	global_load_dword v4, v18, s[18:19] sc1
	global_load_dword v5, v18, s[22:23] sc1
	global_load_dword v6, v18, s[24:25] sc1
	global_load_dword v7, v18, s[38:39] sc1
	global_load_dword v8, v18, s[40:41] sc1
	global_load_dword v9, v18, s[42:43] sc1
	global_load_dword v10, v18, s[44:45] sc1
	global_load_dword v11, v18, s[46:47] sc1
	global_load_dword v12, v18, s[48:49] sc1
	global_load_dword v13, v18, s[50:51] sc1
	global_load_dword v14, v18, s[52:53] sc1
	global_load_dword v15, v18, s[54:55] sc1
	global_load_dword v16, v18, s[56:57] sc1
	s_mov_b64 s[58:59], -1
	s_mov_b64 s[60:61], -1
	s_waitcnt vmcnt(14)
	v_add_u32_e32 v19, v2, v17
	s_waitcnt vmcnt(13)
	v_add_u32_e32 v19, v19, v3
	s_waitcnt vmcnt(12)
	v_add_u32_e32 v19, v19, v4
	s_waitcnt vmcnt(11)
	v_add_u32_e32 v19, v19, v5
	s_waitcnt vmcnt(10)
	v_add_u32_e32 v19, v19, v6
	s_waitcnt vmcnt(9)
	v_add_u32_e32 v19, v19, v7
	s_waitcnt vmcnt(8)
	v_add_u32_e32 v19, v19, v8
	s_waitcnt vmcnt(7)
	v_add_u32_e32 v19, v19, v9
	s_waitcnt vmcnt(6)
	v_add_u32_e32 v19, v19, v10
	s_waitcnt vmcnt(5)
	v_add_u32_e32 v19, v19, v11
	s_waitcnt vmcnt(4)
	v_add_u32_e32 v19, v19, v12
	s_waitcnt vmcnt(3)
	v_add_u32_e32 v19, v19, v13
	s_waitcnt vmcnt(2)
	v_add_u32_e32 v19, v19, v14
	s_waitcnt vmcnt(1)
	v_add_u32_e32 v19, v19, v15
	s_waitcnt vmcnt(0)
	v_add_u32_e32 v19, v19, v16
	v_cmp_eq_u32_e32 vcc, s37, v19
	s_cbranch_vccnz .LBB0_1262
	s_and_b32 s33, s64, 0xff
	s_cmp_eq_u32 s33, 0
	s_mov_b64 s[62:63], -1
	s_nop 0
	s_cbranch_scc0 .LBB0_1267
	global_load_dword v19, v18, s[8:9] sc1
	s_waitcnt vmcnt(0)
	v_cmp_eq_u32_e32 vcc, 0, v19
	s_cbranch_vccnz .LBB0_1269
	s_mov_b64 s[62:63], 0

.LBB0_1281:
	s_and_b32 s33, s37, 0xff
	s_mov_b64 s[38:39], -1
	s_cmp_lg_u32 s33, 0
	s_mov_b64 s[42:43], -1
	s_nop 0
	s_cbranch_scc1 .LBB0_1284
	global_load_dword v4, v2, s[16:17] sc1
	s_waitcnt vmcnt(0)
	v_cmp_eq_u32_e32 vcc, 0, v4
	s_cbranch_vccnz .LBB0_1286
	s_mov_b64 s[42:43], 0
	s_mov_b64 s[40:41], -1

.LBB0_1298:
	s_and_b32 s33, s37, 0xff
	s_cmp_lg_u32 s33, 0
	s_mov_b64 s[40:41], -1
	s_nop 0
	s_cbranch_scc1 .LBB0_1301
	global_load_dword v3, v2, s[16:17] sc1
	s_waitcnt vmcnt(0)
	v_cmp_eq_u32_e32 vcc, 0, v3
	s_cbranch_vccnz .LBB0_1303
	s_mov_b64 s[40:41], 0
	s_mov_b64 s[38:39], -1

.LBB0_1318:
	global_load_dword v17, v18, s[14:15] sc1
	global_load_dword v2, v18, s[16:17] sc1
	global_load_dword v3, v18, s[18:19] sc1
	global_load_dword v4, v18, s[22:23] sc1
	global_load_dword v5, v18, s[24:25] sc1
	global_load_dword v6, v18, s[38:39] sc1
	global_load_dword v7, v18, s[40:41] sc1
	global_load_dword v8, v18, s[42:43] sc1
	global_load_dword v9, v18, s[44:45] sc1
	global_load_dword v10, v18, s[46:47] sc1
	global_load_dword v11, v18, s[48:49] sc1
	global_load_dword v12, v18, s[50:51] sc1
	global_load_dword v13, v18, s[52:53] sc1
	global_load_dword v14, v18, s[54:55] sc1
	global_load_dword v15, v18, s[56:57] sc1
	global_load_dword v16, v18, s[58:59] sc1
	s_mov_b64 s[60:61], -1
	s_mov_b64 s[62:63], -1
	s_waitcnt vmcnt(14)
	v_add_u32_e32 v19, v2, v17
	s_waitcnt vmcnt(13)
	v_add_u32_e32 v19, v19, v3
	s_waitcnt vmcnt(12)
	v_add_u32_e32 v19, v19, v4
	s_waitcnt vmcnt(11)
	v_add_u32_e32 v19, v19, v5
	s_waitcnt vmcnt(10)
	v_add_u32_e32 v19, v19, v6
	s_waitcnt vmcnt(9)
	v_add_u32_e32 v19, v19, v7
	s_waitcnt vmcnt(8)
	v_add_u32_e32 v19, v19, v8
	s_waitcnt vmcnt(7)
	v_add_u32_e32 v19, v19, v9
	s_waitcnt vmcnt(6)
	v_add_u32_e32 v19, v19, v10
	s_waitcnt vmcnt(5)
	v_add_u32_e32 v19, v19, v11
	s_waitcnt vmcnt(4)
	v_add_u32_e32 v19, v19, v12
	s_waitcnt vmcnt(3)
	v_add_u32_e32 v19, v19, v13
	s_waitcnt vmcnt(2)
	v_add_u32_e32 v19, v19, v14
	s_waitcnt vmcnt(1)
	v_add_u32_e32 v19, v19, v15
	s_waitcnt vmcnt(0)
	v_add_u32_e32 v19, v19, v16
	v_cmp_eq_u32_e32 vcc, s66, v19
	s_cbranch_vccnz .LBB0_1317
	s_and_b32 s33, s37, 0xff
	s_cmp_eq_u32 s33, 0
	s_mov_b64 s[64:65], -1
	s_nop 0
	s_cbranch_scc0 .LBB0_1322
	global_load_dword v19, v18, s[12:13] sc1
	s_waitcnt vmcnt(0)
	v_cmp_eq_u32_e32 vcc, 0, v19
	s_cbranch_vccnz .LBB0_1324
	s_mov_b64 s[64:65], 0

.LBB0_1336:
	s_and_b32 s33, s37, 0xff
	s_mov_b64 s[40:41], -1
	s_cmp_lg_u32 s33, 0
	s_mov_b64 s[44:45], -1
	s_nop 0
	s_cbranch_scc1 .LBB0_1339
	global_load_dword v4, v2, s[18:19] sc1
	s_waitcnt vmcnt(0)
	v_cmp_eq_u32_e32 vcc, 0, v4
	s_cbranch_vccnz .LBB0_1341
	s_mov_b64 s[44:45], 0
	s_mov_b64 s[42:43], -1

.LBB0_1353:
	s_and_b32 s33, s37, 0xff
	s_cmp_lg_u32 s33, 0
	s_mov_b64 s[42:43], -1
	s_nop 0
	s_cbranch_scc1 .LBB0_1356
	global_load_dword v3, v2, s[18:19] sc1
	s_waitcnt vmcnt(0)
	v_cmp_eq_u32_e32 vcc, 0, v3
	s_cbranch_vccnz .LBB0_1358
	s_mov_b64 s[42:43], 0
	s_mov_b64 s[40:41], -1

.LBB0_1390:
	global_load_dword v17, v18, s[16:17] sc1
	global_load_dword v2, v18, s[18:19] sc1
	global_load_dword v3, v18, s[22:23] sc1
	global_load_dword v4, v18, s[24:25] sc1
	global_load_dword v5, v18, s[38:39] sc1
	global_load_dword v6, v18, s[40:41] sc1
	global_load_dword v7, v18, s[42:43] sc1
	global_load_dword v8, v18, s[44:45] sc1
	global_load_dword v9, v18, s[46:47] sc1
	global_load_dword v10, v18, s[48:49] sc1
	global_load_dword v11, v18, s[50:51] sc1
	global_load_dword v12, v18, s[52:53] sc1
	global_load_dword v13, v18, s[54:55] sc1
	global_load_dword v14, v18, s[56:57] sc1
	global_load_dword v15, v18, s[58:59] sc1
	global_load_dword v16, v18, s[60:61] sc1
	s_mov_b64 s[62:63], -1
	s_mov_b64 s[64:65], -1
	s_waitcnt vmcnt(14)
	v_add_u32_e32 v19, v2, v17
	s_waitcnt vmcnt(13)
	v_add_u32_e32 v19, v19, v3
	s_waitcnt vmcnt(12)
	v_add_u32_e32 v19, v19, v4
	s_waitcnt vmcnt(11)
	v_add_u32_e32 v19, v19, v5
	s_waitcnt vmcnt(10)
	v_add_u32_e32 v19, v19, v6
	s_waitcnt vmcnt(9)
	v_add_u32_e32 v19, v19, v7
	s_waitcnt vmcnt(8)
	v_add_u32_e32 v19, v19, v8
	s_waitcnt vmcnt(7)
	v_add_u32_e32 v19, v19, v9
	s_waitcnt vmcnt(6)
	v_add_u32_e32 v19, v19, v10
	s_waitcnt vmcnt(5)
	v_add_u32_e32 v19, v19, v11
	s_waitcnt vmcnt(4)
	v_add_u32_e32 v19, v19, v12
	s_waitcnt vmcnt(3)
	v_add_u32_e32 v19, v19, v13
	s_waitcnt vmcnt(2)
	v_add_u32_e32 v19, v19, v14
	s_waitcnt vmcnt(1)
	v_add_u32_e32 v19, v19, v15
	s_waitcnt vmcnt(0)
	v_add_u32_e32 v19, v19, v16
	v_cmp_eq_u32_e32 vcc, s71, v19
	s_cbranch_vccnz .LBB0_1389
	s_and_b32 s33, s37, 0xff
	s_cmp_eq_u32 s33, 0
	s_mov_b64 s[66:67], -1
	s_nop 0
	s_cbranch_scc0 .LBB0_1394
	global_load_dword v19, v18, s[14:15] sc1
	s_waitcnt vmcnt(0)
	v_cmp_eq_u32_e32 vcc, 0, v19
	s_cbranch_vccnz .LBB0_1396
	s_mov_b64 s[66:67], 0

.LBB0_1408:
	s_and_b32 s33, s37, 0xff
	s_mov_b64 s[42:43], -1
	s_cmp_lg_u32 s33, 0
	s_mov_b64 s[46:47], -1
	s_nop 0
	s_cbranch_scc1 .LBB0_1411
	global_load_dword v4, v2, s[22:23] sc1
	s_waitcnt vmcnt(0)
	v_cmp_eq_u32_e32 vcc, 0, v4
	s_cbranch_vccnz .LBB0_1413
	s_mov_b64 s[46:47], 0
	s_mov_b64 s[44:45], -1

.LBB0_1425:
	s_and_b32 s33, s37, 0xff
	s_cmp_lg_u32 s33, 0
	s_mov_b64 s[44:45], -1
	s_nop 0
	s_cbranch_scc1 .LBB0_1428
	global_load_dword v3, v2, s[22:23] sc1
	s_waitcnt vmcnt(0)
	v_cmp_eq_u32_e32 vcc, 0, v3
	s_cbranch_vccnz .LBB0_1430
	s_mov_b64 s[44:45], 0
	s_mov_b64 s[42:43], -1

.LBB0_1576:
	global_load_dword v17, v18, s[16:17] sc1
	global_load_dword v2, v18, s[18:19] sc1
	global_load_dword v3, v18, s[22:23] sc1
	global_load_dword v4, v18, s[24:25] sc1
	global_load_dword v5, v18, s[36:37] sc1
	global_load_dword v6, v18, s[38:39] sc1
	global_load_dword v7, v18, s[40:41] sc1
	global_load_dword v8, v18, s[42:43] sc1
	global_load_dword v9, v18, s[44:45] sc1
	global_load_dword v10, v18, s[46:47] sc1
	global_load_dword v11, v18, s[48:49] sc1
	global_load_dword v12, v18, s[50:51] sc1
	global_load_dword v13, v18, s[52:53] sc1
	global_load_dword v14, v18, s[54:55] sc1
	global_load_dword v15, v18, s[56:57] sc1
	global_load_dword v16, v18, s[58:59] sc1
	s_mov_b64 s[60:61], -1
	s_mov_b64 s[62:63], -1
	s_waitcnt vmcnt(14)
	v_add_u32_e32 v19, v2, v17
	s_waitcnt vmcnt(13)
	v_add_u32_e32 v19, v19, v3
	s_waitcnt vmcnt(12)
	v_add_u32_e32 v19, v19, v4
	s_waitcnt vmcnt(11)
	v_add_u32_e32 v19, v19, v5
	s_waitcnt vmcnt(10)
	v_add_u32_e32 v19, v19, v6
	s_waitcnt vmcnt(9)
	v_add_u32_e32 v19, v19, v7
	s_waitcnt vmcnt(8)
	v_add_u32_e32 v19, v19, v8
	s_waitcnt vmcnt(7)
	v_add_u32_e32 v19, v19, v9
	s_waitcnt vmcnt(6)
	v_add_u32_e32 v19, v19, v10
	s_waitcnt vmcnt(5)
	v_add_u32_e32 v19, v19, v11
	s_waitcnt vmcnt(4)
	v_add_u32_e32 v19, v19, v12
	s_waitcnt vmcnt(3)
	v_add_u32_e32 v19, v19, v13
	s_waitcnt vmcnt(2)
	v_add_u32_e32 v19, v19, v14
	s_waitcnt vmcnt(1)
	v_add_u32_e32 v19, v19, v15
	s_waitcnt vmcnt(0)
	v_add_u32_e32 v19, v19, v16
	v_cmp_eq_u32_e32 vcc, s67, v19
	s_cbranch_vccnz .LBB0_1575
	s_and_b32 s33, s66, 0xff
	s_cmp_eq_u32 s33, 0
	s_mov_b64 s[64:65], -1
	s_nop 0
	s_cbranch_scc0 .LBB0_1580
	global_load_dword v19, v18, s[14:15] sc1
	s_waitcnt vmcnt(0)
	v_cmp_eq_u32_e32 vcc, 0, v19
	s_cbranch_vccnz .LBB0_1582
	s_mov_b64 s[64:65], 0

.LBB0_1594:
	s_and_b32 s33, s46, 0xff
	s_mov_b64 s[40:41], -1
	s_cmp_lg_u32 s33, 0
	s_mov_b64 s[44:45], -1
	s_nop 0
	s_cbranch_scc1 .LBB0_1597
	global_load_dword v4, v2, s[22:23] sc1
	s_waitcnt vmcnt(0)
	v_cmp_eq_u32_e32 vcc, 0, v4
	s_cbranch_vccnz .LBB0_1599
	s_mov_b64 s[44:45], 0
	s_mov_b64 s[42:43], -1

.LBB0_1611:
	s_and_b32 s33, s46, 0xff
	s_cmp_lg_u32 s33, 0
	s_mov_b64 s[42:43], -1
	s_nop 0
	s_cbranch_scc1 .LBB0_1614
	global_load_dword v3, v2, s[22:23] sc1
	s_waitcnt vmcnt(0)
	v_cmp_eq_u32_e32 vcc, 0, v3
	s_cbranch_vccnz .LBB0_1616
	s_mov_b64 s[42:43], 0
	s_mov_b64 s[40:41], -1

.LBB0_1644:
	global_load_dword v16, v17, s[14:15] sc1
	s_waitcnt lgkmcnt(0)
	global_load_dword v1, v17, s[16:17] sc1
	global_load_dword v2, v17, s[18:19] sc1
	global_load_dword v3, v17, s[20:21] sc1
	global_load_dword v4, v17, s[22:23] sc1
	global_load_dword v5, v17, s[24:25] sc1
	global_load_dword v6, v17, s[36:37] sc1
	global_load_dword v7, v17, s[38:39] sc1
	global_load_dword v8, v17, s[40:41] sc1
	global_load_dword v9, v17, s[42:43] sc1
	global_load_dword v10, v17, s[44:45] sc1
	global_load_dword v11, v17, s[46:47] sc1
	global_load_dword v12, v17, s[48:49] sc1
	global_load_dword v13, v17, s[50:51] sc1
	global_load_dword v14, v17, s[52:53] sc1
	global_load_dword v15, v17, s[54:55] sc1
	s_mov_b64 s[56:57], -1
	s_mov_b64 s[58:59], -1
	s_waitcnt vmcnt(14)
	v_add_u32_e32 v18, v1, v16
	s_waitcnt vmcnt(13)
	v_add_u32_e32 v18, v18, v2
	s_waitcnt vmcnt(12)
	v_add_u32_e32 v18, v18, v3
	s_waitcnt vmcnt(11)
	v_add_u32_e32 v18, v18, v4
	s_waitcnt vmcnt(10)
	v_add_u32_e32 v18, v18, v5
	s_waitcnt vmcnt(9)
	v_add_u32_e32 v18, v18, v6
	s_waitcnt vmcnt(8)
	v_add_u32_e32 v18, v18, v7
	s_waitcnt vmcnt(7)
	v_add_u32_e32 v18, v18, v8
	s_waitcnt vmcnt(6)
	v_add_u32_e32 v18, v18, v9
	s_waitcnt vmcnt(5)
	v_add_u32_e32 v18, v18, v10
	s_waitcnt vmcnt(4)
	v_add_u32_e32 v18, v18, v11
	s_waitcnt vmcnt(3)
	v_add_u32_e32 v18, v18, v12
	s_waitcnt vmcnt(2)
	v_add_u32_e32 v18, v18, v13
	s_waitcnt vmcnt(1)
	v_add_u32_e32 v18, v18, v14
	s_waitcnt vmcnt(0)
	v_add_u32_e32 v18, v18, v15
	v_cmp_eq_u32_e32 vcc, s31, v18
	s_cbranch_vccnz .LBB0_1643
	s_and_b32 s56, s33, 0xff
	s_cmp_eq_u32 s56, 0
	s_mov_b64 s[56:57], -1
	s_mov_b64 s[60:61], -1
	s_nop 0
	s_cbranch_scc0 .LBB0_1648
	global_load_dword v18, v17, s[10:11] sc1
	s_waitcnt vmcnt(0)
	v_cmp_eq_u32_e32 vcc, 0, v18
	s_cbranch_vccnz .LBB0_1650
	s_mov_b64 s[60:61], 0

.LBB0_1662:
	s_and_b32 s31, s3, 0xff
	s_mov_b64 s[34:35], -1
	s_cmp_lg_u32 s31, 0
	s_mov_b64 s[38:39], -1
	s_nop 0
	s_cbranch_scc1 .LBB0_1665
	global_load_dword v3, v1, s[18:19] sc1
	s_waitcnt vmcnt(0)
	v_cmp_eq_u32_e32 vcc, 0, v3
	s_cbranch_vccnz .LBB0_1667
	s_mov_b64 s[38:39], 0
	s_mov_b64 s[36:37], -1

.LBB0_1679:
	s_and_b32 s31, s3, 0xff
	s_cmp_lg_u32 s31, 0
	s_mov_b64 s[36:37], -1
	s_nop 0
	s_cbranch_scc1 .LBB0_1682
	global_load_dword v2, v1, s[18:19] sc1
	s_waitcnt vmcnt(0)
	v_cmp_eq_u32_e32 vcc, 0, v2
	s_cbranch_vccnz .LBB0_1684
	s_mov_b64 s[36:37], 0
	s_mov_b64 s[34:35], -1

.LBB0_1730:
	s_nop 0
	global_load_dword v2, v0, s[2:3] offset:32 sc1
	s_waitcnt vmcnt(0)
	v_and_b32_e32 v2, 0xffff0000, v2
	v_cmp_ne_u32_e32 vcc, v2, v1
	s_or_b64 s[4:5], vcc, s[4:5]
	s_andn2_b64 exec, exec, s[4:5]
	s_cbranch_execnz .LBB0_1730
